# nt policy also on the read-once f32 weight loads of the P0 transposes (on top of P1/P6 row loads)
# speedup vs baseline: 1.0700x; 1.0003x over previous
.LBB0_44:
	s_cmp_ge_i32 s20, s10
	s_cbranch_scc1 .LBB0_43
	s_mul_hi_i32 s0, s20, 0x1b4e81b5
	s_lshr_b32 s2, s0, 31
	s_ashr_i32 s0, s0, 7
	s_add_i32 s2, s0, s2
	s_mul_i32 s0, s2, 0x4b0
	s_sub_i32 s83, s20, s0
	s_ashr_i32 s3, s2, 31
	s_cmpk_gt_i32 s83, 0x39f
	s_mov_b64 s[4:5], -1
	s_cbranch_scc0 .LBB0_55
	s_cmpk_gt_u32 s83, 0x49f
	s_cbranch_scc0 .LBB0_52
	s_lshl_b64 s[6:7], s[2:3], 17
	s_lshl_b64 s[4:5], s[2:3], 16
	s_lshl_b32 s0, s83, 6
	s_cmpk_gt_u32 s83, 0x4a7
	s_mov_b64 s[8:9], -1
	s_cbranch_scc0 .LBB0_49
	s_add_u32 s12, s52, s6
	s_addc_u32 s85, s53, s7
	s_add_u32 s8, s21, s4
	s_addc_u32 s9, s22, s5
	s_add_i32 s84, s0, 0x3ed600
	s_and_b32 s86, s84, 0x3fffc0
	v_mov_b32_e32 v20, v154
	s_lshl_b32 s84, s86, 2
	s_add_u32 s84, s12, s84
	v_ashrrev_i32_e32 v2, 6, v20
	v_lshlrev_b32_e32 v0, 2, v20
	s_addc_u32 s85, s85, 0
	v_and_b32_e32 v0, 0xfc, v0
	v_ashrrev_i32_e32 v3, 31, v2
	v_lshl_add_u64 v[4:5], s[84:85], 0, v[0:1]
	v_lshlrev_b64 v[6:7], 11, v[2:3]
	v_lshl_add_u64 v[4:5], v[4:5], 0, v[6:7]
	v_add_co_u32_e32 v6, vcc, s37, v4
	v_ashrrev_i32_e32 v3, 3, v20
	s_nop 0
	v_addc_co_u32_e32 v7, vcc, 0, v5, vcc
	v_add_co_u32_e32 v8, vcc, s76, v4
	v_mul_lo_u32 v2, v2, s36
	s_nop 0
	v_addc_co_u32_e32 v9, vcc, 0, v5, vcc
	v_add_co_u32_e32 v10, vcc, s77, v4
	s_nop 1
	v_addc_co_u32_e32 v11, vcc, 0, v5, vcc
	v_add_co_u32_e32 v12, vcc, s78, v4
	s_nop 1
	v_addc_co_u32_e32 v13, vcc, 0, v5, vcc
	v_add_co_u32_e32 v14, vcc, s79, v4
	s_nop 1
	v_addc_co_u32_e32 v15, vcc, 0, v5, vcc
	v_add_co_u32_e32 v16, vcc, s80, v4
	s_nop 1
	v_addc_co_u32_e32 v17, vcc, 0, v5, vcc
	v_add_co_u32_e32 v18, vcc, s81, v4
	s_nop 1
	v_addc_co_u32_e32 v19, vcc, 0, v5, vcc
	global_load_dword v4, v[4:5], off nt
	s_nop 0
	global_load_dword v5, v[6:7], off nt
	s_nop 0
	global_load_dword v6, v[8:9], off nt
	global_load_dword v7, v[10:11], off nt
	s_nop 0
	global_load_dword v8, v[12:13], off nt
	global_load_dword v9, v[14:15], off nt
	global_load_dword v10, v[16:17], off nt
	global_load_dword v11, v[18:19], off nt
	v_lshlrev_b32_e32 v12, 3, v20
	v_and_b32_e32 v12, 56, v12
	v_lshlrev_b32_e32 v13, 2, v3
	v_add3_u32 v14, 0, v2, v0
	v_mul_u32_u24_e32 v0, 0x104, v12
	v_add3_u32 v13, 0, v0, v13
	v_add_u32_e32 v15, 0x400, v13
	v_add_u32_e32 v2, s86, v3
	v_ashrrev_i32_e32 v3, 31, v2
	v_lshlrev_b64 v[2:3], 7, v[2:3]
	v_lshl_add_u64 v[2:3], s[8:9], 0, v[2:3]
	v_lshlrev_b32_e32 v0, 1, v12
	s_mov_b64 s[8:9], 0
	s_waitcnt vmcnt(7)
	ds_write_b32 v14, v4
	s_waitcnt vmcnt(6)
	ds_write_b32 v14, v5 offset:2080
	s_waitcnt vmcnt(5)
	ds_write_b32 v14, v6 offset:4160
	s_waitcnt vmcnt(4)
	ds_write_b32 v14, v7 offset:6240
	s_waitcnt vmcnt(3)
	ds_write_b32 v14, v8 offset:8320
	s_waitcnt vmcnt(2)
	ds_write_b32 v14, v9 offset:10400
	s_waitcnt vmcnt(1)
	ds_write_b32 v14, v10 offset:12480
	s_waitcnt vmcnt(0)
	ds_write_b32 v14, v11 offset:14560
	s_waitcnt lgkmcnt(0)
	s_barrier
	ds_read2_b32 v[4:5], v15 offset0:134 offset1:199
	ds_read2_b32 v[6:7], v15 offset0:4 offset1:69
	ds_read2_b32 v[8:9], v13 offset0:130 offset1:195
	ds_read2_b32 v[10:11], v13 offset1:65
	v_lshl_add_u64 v[12:13], v[2:3], 0, v[0:1]
	s_waitcnt lgkmcnt(3)
	v_cvt_pk_f16_f32 v5, v4, v5
	s_waitcnt lgkmcnt(2)
	v_cvt_pk_f16_f32 v4, v6, v7
	s_waitcnt lgkmcnt(1)
	v_cvt_pk_f16_f32 v3, v8, v9
	s_waitcnt lgkmcnt(0)
	v_cvt_pk_f16_f32 v2, v10, v11
	global_store_dwordx4 v[12:13], v[2:5], off
	s_barrier
.LBB0_49:
	s_andn2_b64 vcc, exec, s[8:9]
	s_cbranch_vccnz .LBB0_51
	s_add_u32 s6, s48, s6
	s_addc_u32 s7, s49, s7
	s_add_u32 s4, s23, s4
	s_addc_u32 s5, s30, s5
	s_add_i32 s0, s0, 0x3ed800
	s_and_b32 s0, s0, 0x3fffc0
	v_mov_b32_e32 v20, v154
	s_lshl_b32 s8, s0, 2
	s_add_u32 s6, s6, s8
	v_ashrrev_i32_e32 v2, 6, v20
	v_lshlrev_b32_e32 v0, 2, v20
	s_addc_u32 s7, s7, 0
	v_and_b32_e32 v0, 0xfc, v0
	v_ashrrev_i32_e32 v3, 31, v2
	v_lshl_add_u64 v[4:5], s[6:7], 0, v[0:1]
	v_lshlrev_b64 v[6:7], 11, v[2:3]
	v_lshl_add_u64 v[4:5], v[4:5], 0, v[6:7]
	v_add_co_u32_e32 v6, vcc, s37, v4
	v_ashrrev_i32_e32 v3, 3, v20
	s_nop 0
	v_addc_co_u32_e32 v7, vcc, 0, v5, vcc
	v_add_co_u32_e32 v8, vcc, s76, v4
	v_mul_lo_u32 v2, v2, s36
	s_nop 0
	v_addc_co_u32_e32 v9, vcc, 0, v5, vcc
	v_add_co_u32_e32 v10, vcc, s77, v4
	s_nop 1
	v_addc_co_u32_e32 v11, vcc, 0, v5, vcc
	v_add_co_u32_e32 v12, vcc, s78, v4
	s_nop 1
	v_addc_co_u32_e32 v13, vcc, 0, v5, vcc
	v_add_co_u32_e32 v14, vcc, s79, v4
	s_nop 1
	v_addc_co_u32_e32 v15, vcc, 0, v5, vcc
	v_add_co_u32_e32 v16, vcc, s80, v4
	s_nop 1
	v_addc_co_u32_e32 v17, vcc, 0, v5, vcc
	v_add_co_u32_e32 v18, vcc, s81, v4
	s_nop 1
	v_addc_co_u32_e32 v19, vcc, 0, v5, vcc
	global_load_dword v4, v[4:5], off nt
	s_nop 0
	global_load_dword v5, v[6:7], off nt
	s_nop 0
	global_load_dword v6, v[8:9], off nt
	global_load_dword v7, v[10:11], off nt
	s_nop 0
	global_load_dword v8, v[12:13], off nt
	global_load_dword v9, v[14:15], off nt
	global_load_dword v10, v[16:17], off nt
	global_load_dword v11, v[18:19], off nt
	v_lshlrev_b32_e32 v12, 3, v20
	v_and_b32_e32 v12, 56, v12
	v_lshlrev_b32_e32 v13, 2, v3
	v_add3_u32 v14, 0, v2, v0
	v_mul_u32_u24_e32 v0, 0x104, v12
	v_add3_u32 v13, 0, v0, v13
	v_add_u32_e32 v15, 0x400, v13
	v_add_u32_e32 v2, s0, v3
	v_ashrrev_i32_e32 v3, 31, v2
	v_lshlrev_b64 v[2:3], 7, v[2:3]
	v_lshl_add_u64 v[2:3], s[4:5], 0, v[2:3]
	v_lshlrev_b32_e32 v0, 1, v12
	s_waitcnt vmcnt(7)
	ds_write_b32 v14, v4
	s_waitcnt vmcnt(6)
	ds_write_b32 v14, v5 offset:2080
	s_waitcnt vmcnt(5)
	ds_write_b32 v14, v6 offset:4160
	s_waitcnt vmcnt(4)
	ds_write_b32 v14, v7 offset:6240
	s_waitcnt vmcnt(3)
	ds_write_b32 v14, v8 offset:8320
	s_waitcnt vmcnt(2)
	ds_write_b32 v14, v9 offset:10400
	s_waitcnt vmcnt(1)
	ds_write_b32 v14, v10 offset:12480
	s_waitcnt vmcnt(0)
	ds_write_b32 v14, v11 offset:14560
	s_waitcnt lgkmcnt(0)
	s_barrier
	ds_read2_b32 v[4:5], v15 offset0:134 offset1:199
	ds_read2_b32 v[6:7], v15 offset0:4 offset1:69
	ds_read2_b32 v[8:9], v13 offset0:130 offset1:195
	ds_read2_b32 v[10:11], v13 offset1:65
	v_lshl_add_u64 v[12:13], v[2:3], 0, v[0:1]
	s_waitcnt lgkmcnt(3)
	v_cvt_pk_f16_f32 v5, v4, v5
	s_waitcnt lgkmcnt(2)
	v_cvt_pk_f16_f32 v4, v6, v7
	s_waitcnt lgkmcnt(1)
	v_cvt_pk_f16_f32 v3, v8, v9
	s_waitcnt lgkmcnt(0)
	v_cvt_pk_f16_f32 v2, v10, v11
	global_store_dwordx4 v[12:13], v[2:5], off
	s_barrier

.LBB0_52:
	s_andn2_b64 vcc, exec, s[4:5]
	s_cbranch_vccnz .LBB0_54
	s_lshl_b64 s[4:5], s[2:3], 22
	s_add_u32 s0, s72, s4
	s_addc_u32 s7, s73, s5
	s_lshl_b64 s[4:5], s[2:3], 21
	s_add_u32 s4, s31, s4
	s_addc_u32 s5, s34, s5
	s_lshl_b32 s3, s83, 2
	s_addk_i32 s3, 0x180
	s_lshl_b32 s6, s83, 6
	v_mov_b32_e32 v20, v154
	s_and_b32 s3, s3, 0x3c0
	s_and_b32 s8, s6, 0x3c0
	s_lshl_b32 s6, s8, 2
	v_ashrrev_i32_e32 v21, 6, v20
	v_add_u32_e32 v4, s3, v21
	s_add_u32 s6, s0, s6
	v_lshlrev_b32_e32 v0, 2, v20
	v_ashrrev_i32_e32 v5, 31, v4
	v_add_u32_e32 v8, 8, v4
	v_add_u32_e32 v10, 16, v4
	s_addc_u32 s7, s7, 0
	v_and_b32_e32 v0, 0xfc, v0
	v_lshlrev_b64 v[6:7], 12, v[4:5]
	v_ashrrev_i32_e32 v9, 31, v8
	v_ashrrev_i32_e32 v11, 31, v10
	v_add_u32_e32 v12, 24, v4
	v_add_u32_e32 v14, 32, v4
	v_add_u32_e32 v16, 40, v4
	v_add_u32_e32 v18, 48, v4
	v_add_u32_e32 v4, 56, v4
	v_lshl_add_u64 v[2:3], s[6:7], 0, v[0:1]
	v_lshlrev_b64 v[8:9], 12, v[8:9]
	v_lshlrev_b64 v[10:11], 12, v[10:11]
	v_ashrrev_i32_e32 v13, 31, v12
	v_ashrrev_i32_e32 v15, 31, v14
	v_ashrrev_i32_e32 v17, 31, v16
	v_ashrrev_i32_e32 v19, 31, v18
	v_ashrrev_i32_e32 v5, 31, v4
	v_lshl_add_u64 v[6:7], v[2:3], 0, v[6:7]
	v_lshl_add_u64 v[8:9], v[2:3], 0, v[8:9]
	v_lshl_add_u64 v[10:11], v[2:3], 0, v[10:11]
	v_lshlrev_b64 v[12:13], 12, v[12:13]
	v_lshlrev_b64 v[14:15], 12, v[14:15]
	v_lshlrev_b64 v[16:17], 12, v[16:17]
	v_lshlrev_b64 v[18:19], 12, v[18:19]
	v_lshlrev_b64 v[4:5], 12, v[4:5]
	v_lshl_add_u64 v[12:13], v[2:3], 0, v[12:13]
	v_lshl_add_u64 v[14:15], v[2:3], 0, v[14:15]
	v_lshl_add_u64 v[16:17], v[2:3], 0, v[16:17]
	v_lshl_add_u64 v[18:19], v[2:3], 0, v[18:19]
	v_lshl_add_u64 v[2:3], v[2:3], 0, v[4:5]
	global_load_dword v4, v[6:7], off nt
	global_load_dword v5, v[8:9], off nt
	s_nop 0
	global_load_dword v6, v[10:11], off nt
	global_load_dword v7, v[12:13], off nt
	global_load_dword v8, v[14:15], off nt
	global_load_dword v9, v[16:17], off nt
	s_nop 0
	global_load_dword v10, v[18:19], off nt
	global_load_dword v11, v[2:3], off nt
	v_lshlrev_b32_e32 v3, 3, v20
	v_ashrrev_i32_e32 v2, 3, v20
	v_mul_lo_u32 v12, v21, s36
	v_and_b32_e32 v13, 56, v3
	v_lshlrev_b32_e32 v3, 2, v2
	v_add3_u32 v12, 0, v12, v0
	v_mul_u32_u24_e32 v0, 0x104, v13
	v_add3_u32 v14, 0, v0, v3
	v_add_u32_e32 v15, 0x400, v14
	v_add_u32_e32 v2, s8, v2
	v_ashrrev_i32_e32 v3, 31, v2
	v_lshlrev_b64 v[2:3], 11, v[2:3]
	s_lshl_b32 s0, s3, 1
	v_lshl_add_u64 v[2:3], s[4:5], 0, v[2:3]
	v_lshlrev_b32_e32 v0, 1, v13
	v_lshl_add_u64 v[2:3], v[2:3], 0, s[0:1]
	s_waitcnt vmcnt(7)
	ds_write_b32 v12, v4
	s_waitcnt vmcnt(6)
	ds_write_b32 v12, v5 offset:2080
	s_waitcnt vmcnt(5)
	ds_write_b32 v12, v6 offset:4160
	s_waitcnt vmcnt(4)
	ds_write_b32 v12, v7 offset:6240
	s_waitcnt vmcnt(3)
	ds_write_b32 v12, v8 offset:8320
	s_waitcnt vmcnt(2)
	ds_write_b32 v12, v9 offset:10400
	s_waitcnt vmcnt(1)
	ds_write_b32 v12, v10 offset:12480
	s_waitcnt vmcnt(0)
	ds_write_b32 v12, v11 offset:14560
	s_waitcnt lgkmcnt(0)
	s_barrier
	ds_read2_b32 v[4:5], v15 offset0:134 offset1:199
	ds_read2_b32 v[6:7], v15 offset0:4 offset1:69
	ds_read2_b32 v[8:9], v14 offset0:130 offset1:195
	ds_read2_b32 v[10:11], v14 offset1:65
	v_lshl_add_u64 v[12:13], v[2:3], 0, v[0:1]
	s_waitcnt lgkmcnt(3)
	v_cvt_pk_f16_f32 v5, v4, v5
	s_waitcnt lgkmcnt(2)
	v_cvt_pk_f16_f32 v4, v6, v7
	s_waitcnt lgkmcnt(1)
	v_cvt_pk_f16_f32 v3, v8, v9
	s_waitcnt lgkmcnt(0)
	v_cvt_pk_f16_f32 v2, v10, v11
	global_store_dwordx4 v[12:13], v[2:5], off
	s_barrier

.LBB0_55:
	s_andn2_b64 vcc, exec, s[4:5]
	s_cbranch_vccnz .LBB0_42
	s_mul_i32 s3, s2, 0xe80000
	s_mul_hi_i32 s0, s2, 0xe80000
	s_add_u32 s5, s42, s3
	s_addc_u32 s0, s43, s0
	s_mul_hi_i32 s3, s2, 0x780000
	s_mul_i32 s2, s2, 0x780000
	s_add_u32 s2, s14, s2
	s_mul_i32 s4, s83, 0x469f
	s_addc_u32 s3, s15, s3
	s_lshr_b32 s6, s4, 31
	s_ashr_i32 s4, s4, 20
	s_add_i32 s4, s4, s6
	s_sext_i32_i16 s6, s4
	s_mul_i32 s4, s4, 58
	s_sub_i32 s4, s83, s4
	s_sext_i32_i16 s7, s4
	s_lshl_b32 s4, s6, 6
	s_lshl_b32 s6, s7, 6
	s_ashr_i32 s7, s6, 31
	v_mov_b32_e32 v18, v154
	s_lshl_b64 s[8:9], s[6:7], 2
	s_add_u32 s8, s5, s8
	v_ashrrev_i32_e32 v19, 6, v18
	v_lshlrev_b32_e32 v0, 2, v18
	s_addc_u32 s9, s0, s9
	v_and_b32_e32 v0, 0xfc, v0
	v_add_u32_e32 v20, s4, v19
	v_lshl_add_u64 v[2:3], s[8:9], 0, v[0:1]
	v_add_u32_e32 v6, 8, v20
	v_add_u32_e32 v8, 16, v20
	v_add_u32_e32 v10, 24, v20
	v_mad_i64_i32 v[4:5], s[8:9], v20, s82, v[2:3]
	v_mad_i64_i32 v[6:7], s[8:9], v6, s82, v[2:3]
	v_mad_i64_i32 v[8:9], s[8:9], v8, s82, v[2:3]
	v_mad_i64_i32 v[10:11], s[8:9], v10, s82, v[2:3]
	v_add_u32_e32 v12, 32, v20
	v_add_u32_e32 v14, 40, v20
	v_add_u32_e32 v16, 48, v20
	v_add_u32_e32 v20, 56, v20
	v_mad_i64_i32 v[12:13], s[8:9], v12, s82, v[2:3]
	v_mad_i64_i32 v[14:15], s[8:9], v14, s82, v[2:3]
	v_mad_i64_i32 v[16:17], s[8:9], v16, s82, v[2:3]
	v_mad_i64_i32 v[2:3], s[8:9], v20, s82, v[2:3]
	global_load_dword v4, v[4:5], off nt
	s_nop 0
	global_load_dword v5, v[6:7], off nt
	s_nop 0
	global_load_dword v6, v[8:9], off nt
	global_load_dword v7, v[10:11], off nt
	s_nop 0
	global_load_dword v8, v[12:13], off nt
	global_load_dword v9, v[14:15], off nt
	global_load_dword v10, v[16:17], off nt
	global_load_dword v11, v[2:3], off nt
	v_lshlrev_b32_e32 v3, 3, v18
	v_ashrrev_i32_e32 v2, 3, v18
	v_mul_lo_u32 v12, v19, s36
	v_and_b32_e32 v13, 56, v3
	v_lshlrev_b32_e32 v3, 2, v2
	v_add3_u32 v12, 0, v12, v0
	v_mul_u32_u24_e32 v0, 0x104, v13
	v_add3_u32 v14, 0, v0, v3
	v_add_u32_e32 v15, 0x400, v14
	v_add_u32_e32 v2, s6, v2
	v_ashrrev_i32_e32 v3, 31, v2
	v_lshlrev_b64 v[2:3], 11, v[2:3]
	v_lshl_add_u64 v[2:3], s[2:3], 0, v[2:3]
	s_ashr_i32 s5, s4, 31
	v_lshl_add_u64 v[2:3], s[4:5], 1, v[2:3]
	v_lshlrev_b32_e32 v0, 1, v13
	s_waitcnt vmcnt(7)
	ds_write_b32 v12, v4
	s_waitcnt vmcnt(6)
	ds_write_b32 v12, v5 offset:2080
	s_waitcnt vmcnt(5)
	ds_write_b32 v12, v6 offset:4160
	s_waitcnt vmcnt(4)
	ds_write_b32 v12, v7 offset:6240
	s_waitcnt vmcnt(3)
	ds_write_b32 v12, v8 offset:8320
	s_waitcnt vmcnt(2)
	ds_write_b32 v12, v9 offset:10400
	s_waitcnt vmcnt(1)
	ds_write_b32 v12, v10 offset:12480
	s_waitcnt vmcnt(0)
	ds_write_b32 v12, v11 offset:14560
	s_waitcnt lgkmcnt(0)
	s_barrier
	ds_read2_b32 v[4:5], v15 offset0:134 offset1:199
	ds_read2_b32 v[6:7], v15 offset0:4 offset1:69
	ds_read2_b32 v[8:9], v14 offset0:130 offset1:195
	ds_read2_b32 v[10:11], v14 offset1:65
	v_lshl_add_u64 v[12:13], v[2:3], 0, v[0:1]
	s_waitcnt lgkmcnt(3)
	v_cvt_pk_f16_f32 v5, v4, v5
	s_waitcnt lgkmcnt(2)
	v_cvt_pk_f16_f32 v4, v6, v7
	s_waitcnt lgkmcnt(1)
	v_cvt_pk_f16_f32 v3, v8, v9
	s_waitcnt lgkmcnt(0)
	v_cvt_pk_f16_f32 v2, v10, v11
	global_store_dwordx4 v[12:13], v[2:5], off
	s_barrier
	s_branch .LBB0_42

.LBB0_60:
	s_mul_hi_i32 s0, s10, 0x1b4e81b5
	s_lshr_b32 s2, s0, 31
	s_ashr_i32 s0, s0, 7
	s_add_i32 s2, s0, s2
	s_mul_i32 s0, s2, 0xfffffb50
	s_add_i32 s84, s10, s0
	s_ashr_i32 s3, s2, 31
	s_cmpk_gt_i32 s84, 0x39f
	s_mov_b64 s[4:5], -1
	s_cbranch_scc0 .LBB0_70
	s_cmpk_gt_u32 s84, 0x49f
	s_cbranch_scc0 .LBB0_67
	s_lshl_b64 s[6:7], s[2:3], 17
	s_lshl_b64 s[4:5], s[2:3], 16
	s_cmpk_gt_u32 s84, 0x4a7
	s_mov_b64 s[8:9], -1
	s_mul_i32 s0, s2, 0xfffed400
	s_cbranch_scc0 .LBB0_64
	s_add_u32 s12, s52, s6
	s_addc_u32 s85, s53, s7
	s_add_u32 s8, s11, s4
	s_addc_u32 s9, s20, s5
	s_add_i32 s86, s31, s0
	s_add_i32 s86, s86, 0x3ed600
	s_and_b32 s88, s86, 0x3fffc0
	v_mov_b32_e32 v20, v154
	s_lshl_b32 s86, s88, 2
	s_add_u32 s86, s12, s86
	v_ashrrev_i32_e32 v2, 6, v20
	v_lshlrev_b32_e32 v0, 2, v20
	s_addc_u32 s87, s85, 0
	v_and_b32_e32 v0, 0xfc, v0
	v_ashrrev_i32_e32 v3, 31, v2
	v_lshl_add_u64 v[4:5], s[86:87], 0, v[0:1]
	v_lshlrev_b64 v[6:7], 11, v[2:3]
	v_lshl_add_u64 v[4:5], v[4:5], 0, v[6:7]
	v_add_co_u32_e32 v6, vcc, s76, v4
	v_ashrrev_i32_e32 v3, 3, v20
	s_nop 0
	v_addc_co_u32_e32 v7, vcc, 0, v5, vcc
	v_add_co_u32_e32 v8, vcc, s77, v4
	v_mul_lo_u32 v2, v2, s37
	s_nop 0
	v_addc_co_u32_e32 v9, vcc, 0, v5, vcc
	v_add_co_u32_e32 v10, vcc, s78, v4
	s_nop 1
	v_addc_co_u32_e32 v11, vcc, 0, v5, vcc
	v_add_co_u32_e32 v12, vcc, s79, v4
	s_nop 1
	v_addc_co_u32_e32 v13, vcc, 0, v5, vcc
	v_add_co_u32_e32 v14, vcc, s80, v4
	s_nop 1
	v_addc_co_u32_e32 v15, vcc, 0, v5, vcc
	v_add_co_u32_e32 v16, vcc, s81, v4
	s_nop 1
	v_addc_co_u32_e32 v17, vcc, 0, v5, vcc
	v_add_co_u32_e32 v18, vcc, s82, v4
	s_nop 1
	v_addc_co_u32_e32 v19, vcc, 0, v5, vcc
	global_load_dword v4, v[4:5], off nt
	s_nop 0
	global_load_dword v5, v[6:7], off nt
	s_nop 0
	global_load_dword v6, v[8:9], off nt
	global_load_dword v7, v[10:11], off nt
	s_nop 0
	global_load_dword v8, v[12:13], off nt
	global_load_dword v9, v[14:15], off nt
	global_load_dword v10, v[16:17], off nt
	global_load_dword v11, v[18:19], off nt
	v_lshlrev_b32_e32 v12, 3, v20
	v_and_b32_e32 v12, 56, v12
	v_lshlrev_b32_e32 v13, 2, v3
	v_add3_u32 v14, 0, v2, v0
	v_mul_u32_u24_e32 v0, 0x104, v12
	v_add3_u32 v13, 0, v0, v13
	v_add_u32_e32 v15, 0x400, v13
	v_add_u32_e32 v2, s88, v3
	v_ashrrev_i32_e32 v3, 31, v2
	v_lshlrev_b64 v[2:3], 7, v[2:3]
	v_lshl_add_u64 v[2:3], s[8:9], 0, v[2:3]
	v_lshlrev_b32_e32 v0, 1, v12
	v_readlane_b32 s88, v250, 4
	v_readlane_b32 s89, v250, 5
	s_mov_b64 s[8:9], 0
	s_waitcnt vmcnt(7)
	ds_write_b32 v14, v4
	s_waitcnt vmcnt(6)
	ds_write_b32 v14, v5 offset:2080
	s_waitcnt vmcnt(5)
	ds_write_b32 v14, v6 offset:4160
	s_waitcnt vmcnt(4)
	ds_write_b32 v14, v7 offset:6240
	s_waitcnt vmcnt(3)
	ds_write_b32 v14, v8 offset:8320
	s_waitcnt vmcnt(2)
	ds_write_b32 v14, v9 offset:10400
	s_waitcnt vmcnt(1)
	ds_write_b32 v14, v10 offset:12480
	s_waitcnt vmcnt(0)
	ds_write_b32 v14, v11 offset:14560
	s_waitcnt lgkmcnt(0)
	s_barrier
	ds_read2_b32 v[4:5], v15 offset0:134 offset1:199
	ds_read2_b32 v[6:7], v15 offset0:4 offset1:69
	ds_read2_b32 v[8:9], v13 offset0:130 offset1:195
	ds_read2_b32 v[10:11], v13 offset1:65
	v_lshl_add_u64 v[12:13], v[2:3], 0, v[0:1]
	s_waitcnt lgkmcnt(3)
	v_cvt_pk_f16_f32 v5, v4, v5
	s_waitcnt lgkmcnt(2)
	v_cvt_pk_f16_f32 v4, v6, v7
	s_waitcnt lgkmcnt(1)
	v_cvt_pk_f16_f32 v3, v8, v9
	s_waitcnt lgkmcnt(0)
	v_cvt_pk_f16_f32 v2, v10, v11
	global_store_dwordx4 v[12:13], v[2:5], off
	s_barrier
.LBB0_64:
	s_andn2_b64 vcc, exec, s[8:9]
	s_cbranch_vccnz .LBB0_66
	s_add_u32 s6, s48, s6
	s_addc_u32 s7, s49, s7
	s_add_u32 s4, s21, s4
	s_addc_u32 s5, s22, s5
	s_add_i32 s0, s31, s0
	s_add_i32 s0, s0, 0x3ed800
	s_and_b32 s0, s0, 0x3fffc0
	v_mov_b32_e32 v20, v154
	s_lshl_b32 s8, s0, 2
	s_add_u32 s6, s6, s8
	v_ashrrev_i32_e32 v2, 6, v20
	v_lshlrev_b32_e32 v0, 2, v20
	s_addc_u32 s7, s7, 0
	v_and_b32_e32 v0, 0xfc, v0
	v_ashrrev_i32_e32 v3, 31, v2
	v_lshl_add_u64 v[4:5], s[6:7], 0, v[0:1]
	v_lshlrev_b64 v[6:7], 11, v[2:3]
	v_lshl_add_u64 v[4:5], v[4:5], 0, v[6:7]
	v_add_co_u32_e32 v6, vcc, s76, v4
	v_ashrrev_i32_e32 v3, 3, v20
	s_nop 0
	v_addc_co_u32_e32 v7, vcc, 0, v5, vcc
	v_add_co_u32_e32 v8, vcc, s77, v4
	v_mul_lo_u32 v2, v2, s37
	s_nop 0
	v_addc_co_u32_e32 v9, vcc, 0, v5, vcc
	v_add_co_u32_e32 v10, vcc, s78, v4
	s_nop 1
	v_addc_co_u32_e32 v11, vcc, 0, v5, vcc
	v_add_co_u32_e32 v12, vcc, s79, v4
	s_nop 1
	v_addc_co_u32_e32 v13, vcc, 0, v5, vcc
	v_add_co_u32_e32 v14, vcc, s80, v4
	s_nop 1
	v_addc_co_u32_e32 v15, vcc, 0, v5, vcc
	v_add_co_u32_e32 v16, vcc, s81, v4
	s_nop 1
	v_addc_co_u32_e32 v17, vcc, 0, v5, vcc
	v_add_co_u32_e32 v18, vcc, s82, v4
	s_nop 1
	v_addc_co_u32_e32 v19, vcc, 0, v5, vcc
	global_load_dword v4, v[4:5], off nt
	s_nop 0
	global_load_dword v5, v[6:7], off nt
	s_nop 0
	global_load_dword v6, v[8:9], off nt
	global_load_dword v7, v[10:11], off nt
	s_nop 0
	global_load_dword v8, v[12:13], off nt
	global_load_dword v9, v[14:15], off nt
	global_load_dword v10, v[16:17], off nt
	global_load_dword v11, v[18:19], off nt
	v_lshlrev_b32_e32 v12, 3, v20
	v_and_b32_e32 v12, 56, v12
	v_lshlrev_b32_e32 v13, 2, v3
	v_add3_u32 v14, 0, v2, v0
	v_mul_u32_u24_e32 v0, 0x104, v12
	v_add3_u32 v13, 0, v0, v13
	v_add_u32_e32 v15, 0x400, v13
	v_add_u32_e32 v2, s0, v3
	v_ashrrev_i32_e32 v3, 31, v2
	v_lshlrev_b64 v[2:3], 7, v[2:3]
	v_lshl_add_u64 v[2:3], s[4:5], 0, v[2:3]
	v_lshlrev_b32_e32 v0, 1, v12
	s_waitcnt vmcnt(7)
	ds_write_b32 v14, v4
	s_waitcnt vmcnt(6)
	ds_write_b32 v14, v5 offset:2080
	s_waitcnt vmcnt(5)
	ds_write_b32 v14, v6 offset:4160
	s_waitcnt vmcnt(4)
	ds_write_b32 v14, v7 offset:6240
	s_waitcnt vmcnt(3)
	ds_write_b32 v14, v8 offset:8320
	s_waitcnt vmcnt(2)
	ds_write_b32 v14, v9 offset:10400
	s_waitcnt vmcnt(1)
	ds_write_b32 v14, v10 offset:12480
	s_waitcnt vmcnt(0)
	ds_write_b32 v14, v11 offset:14560
	s_waitcnt lgkmcnt(0)
	s_barrier
	ds_read2_b32 v[4:5], v15 offset0:134 offset1:199
	ds_read2_b32 v[6:7], v15 offset0:4 offset1:69
	ds_read2_b32 v[8:9], v13 offset0:130 offset1:195
	ds_read2_b32 v[10:11], v13 offset1:65
	v_lshl_add_u64 v[12:13], v[2:3], 0, v[0:1]
	s_waitcnt lgkmcnt(3)
	v_cvt_pk_f16_f32 v5, v4, v5
	s_waitcnt lgkmcnt(2)
	v_cvt_pk_f16_f32 v4, v6, v7
	s_waitcnt lgkmcnt(1)
	v_cvt_pk_f16_f32 v3, v8, v9
	s_waitcnt lgkmcnt(0)
	v_cvt_pk_f16_f32 v2, v10, v11
	global_store_dwordx4 v[12:13], v[2:5], off
	s_barrier

.LBB0_67:
	s_andn2_b64 vcc, exec, s[4:5]
	s_cbranch_vccnz .LBB0_69
	s_lshl_b64 s[4:5], s[2:3], 22
	s_add_u32 s0, s72, s4
	s_addc_u32 s7, s73, s5
	s_lshl_b64 s[4:5], s[2:3], 21
	s_add_u32 s4, s23, s4
	s_mul_i32 s3, s2, 0xffffed40
	s_addc_u32 s5, s30, s5
	s_add_i32 s3, s35, s3
	v_mov_b32_e32 v20, v154
	s_and_b32 s3, s3, 0x3c0
	s_and_b32 s8, s31, 0x3c0
	s_lshl_b32 s6, s8, 2
	v_ashrrev_i32_e32 v21, 6, v20
	v_add_u32_e32 v4, s3, v21
	s_add_u32 s6, s0, s6
	v_lshlrev_b32_e32 v0, 2, v20
	v_ashrrev_i32_e32 v5, 31, v4
	v_add_u32_e32 v8, 8, v4
	v_add_u32_e32 v10, 16, v4
	s_addc_u32 s7, s7, 0
	v_and_b32_e32 v0, 0xfc, v0
	v_lshlrev_b64 v[6:7], 12, v[4:5]
	v_ashrrev_i32_e32 v9, 31, v8
	v_ashrrev_i32_e32 v11, 31, v10
	v_add_u32_e32 v12, 24, v4
	v_add_u32_e32 v14, 32, v4
	v_add_u32_e32 v16, 40, v4
	v_add_u32_e32 v18, 48, v4
	v_add_u32_e32 v4, 56, v4
	v_lshl_add_u64 v[2:3], s[6:7], 0, v[0:1]
	v_lshlrev_b64 v[8:9], 12, v[8:9]
	v_lshlrev_b64 v[10:11], 12, v[10:11]
	v_ashrrev_i32_e32 v13, 31, v12
	v_ashrrev_i32_e32 v15, 31, v14
	v_ashrrev_i32_e32 v17, 31, v16
	v_ashrrev_i32_e32 v19, 31, v18
	v_ashrrev_i32_e32 v5, 31, v4
	v_lshl_add_u64 v[6:7], v[2:3], 0, v[6:7]
	v_lshl_add_u64 v[8:9], v[2:3], 0, v[8:9]
	v_lshl_add_u64 v[10:11], v[2:3], 0, v[10:11]
	v_lshlrev_b64 v[12:13], 12, v[12:13]
	v_lshlrev_b64 v[14:15], 12, v[14:15]
	v_lshlrev_b64 v[16:17], 12, v[16:17]
	v_lshlrev_b64 v[18:19], 12, v[18:19]
	v_lshlrev_b64 v[4:5], 12, v[4:5]
	v_lshl_add_u64 v[12:13], v[2:3], 0, v[12:13]
	v_lshl_add_u64 v[14:15], v[2:3], 0, v[14:15]
	v_lshl_add_u64 v[16:17], v[2:3], 0, v[16:17]
	v_lshl_add_u64 v[18:19], v[2:3], 0, v[18:19]
	v_lshl_add_u64 v[2:3], v[2:3], 0, v[4:5]
	global_load_dword v4, v[6:7], off nt
	global_load_dword v5, v[8:9], off nt
	s_nop 0
	global_load_dword v6, v[10:11], off nt
	global_load_dword v7, v[12:13], off nt
	global_load_dword v8, v[14:15], off nt
	global_load_dword v9, v[16:17], off nt
	s_nop 0
	global_load_dword v10, v[18:19], off nt
	global_load_dword v11, v[2:3], off nt
	v_lshlrev_b32_e32 v3, 3, v20
	v_ashrrev_i32_e32 v2, 3, v20
	v_mul_lo_u32 v12, v21, s37
	v_and_b32_e32 v13, 56, v3
	v_lshlrev_b32_e32 v3, 2, v2
	v_add3_u32 v12, 0, v12, v0
	v_mul_u32_u24_e32 v0, 0x104, v13
	v_add3_u32 v14, 0, v0, v3
	v_add_u32_e32 v15, 0x400, v14
	v_add_u32_e32 v2, s8, v2
	v_ashrrev_i32_e32 v3, 31, v2
	v_lshlrev_b64 v[2:3], 11, v[2:3]
	s_lshl_b32 s0, s3, 1
	v_lshl_add_u64 v[2:3], s[4:5], 0, v[2:3]
	v_lshlrev_b32_e32 v0, 1, v13
	v_lshl_add_u64 v[2:3], v[2:3], 0, s[0:1]
	s_waitcnt vmcnt(7)
	ds_write_b32 v12, v4
	s_waitcnt vmcnt(6)
	ds_write_b32 v12, v5 offset:2080
	s_waitcnt vmcnt(5)
	ds_write_b32 v12, v6 offset:4160
	s_waitcnt vmcnt(4)
	ds_write_b32 v12, v7 offset:6240
	s_waitcnt vmcnt(3)
	ds_write_b32 v12, v8 offset:8320
	s_waitcnt vmcnt(2)
	ds_write_b32 v12, v9 offset:10400
	s_waitcnt vmcnt(1)
	ds_write_b32 v12, v10 offset:12480
	s_waitcnt vmcnt(0)
	ds_write_b32 v12, v11 offset:14560
	s_waitcnt lgkmcnt(0)
	s_barrier
	ds_read2_b32 v[4:5], v15 offset0:134 offset1:199
	ds_read2_b32 v[6:7], v15 offset0:4 offset1:69
	ds_read2_b32 v[8:9], v14 offset0:130 offset1:195
	ds_read2_b32 v[10:11], v14 offset1:65
	v_lshl_add_u64 v[12:13], v[2:3], 0, v[0:1]
	s_waitcnt lgkmcnt(3)
	v_cvt_pk_f16_f32 v5, v4, v5
	s_waitcnt lgkmcnt(2)
	v_cvt_pk_f16_f32 v4, v6, v7
	s_waitcnt lgkmcnt(1)
	v_cvt_pk_f16_f32 v3, v8, v9
	s_waitcnt lgkmcnt(0)
	v_cvt_pk_f16_f32 v2, v10, v11
	global_store_dwordx4 v[12:13], v[2:5], off
	s_barrier

.LBB0_70:
	s_andn2_b64 vcc, exec, s[4:5]
	s_cbranch_vccnz .LBB0_59
	s_mul_i32 s3, s2, 0xe80000
	s_mul_hi_i32 s0, s2, 0xe80000
	s_add_u32 s5, s42, s3
	s_addc_u32 s0, s43, s0
	s_mul_hi_i32 s3, s2, 0x780000
	s_mul_i32 s2, s2, 0x780000
	s_add_u32 s2, s14, s2
	s_mul_i32 s4, s84, 0x469f
	s_addc_u32 s3, s15, s3
	s_lshr_b32 s6, s4, 31
	s_ashr_i32 s4, s4, 20
	s_add_i32 s4, s4, s6
	s_sext_i32_i16 s6, s4
	s_mul_i32 s4, s4, 58
	s_sub_i32 s4, s84, s4
	s_sext_i32_i16 s7, s4
	s_lshl_b32 s4, s6, 6
	s_lshl_b32 s6, s7, 6
	s_ashr_i32 s7, s6, 31
	v_mov_b32_e32 v18, v154
	s_lshl_b64 s[8:9], s[6:7], 2
	s_add_u32 s8, s5, s8
	v_ashrrev_i32_e32 v19, 6, v18
	v_lshlrev_b32_e32 v0, 2, v18
	s_addc_u32 s9, s0, s9
	v_and_b32_e32 v0, 0xfc, v0
	v_add_u32_e32 v20, s4, v19
	v_lshl_add_u64 v[2:3], s[8:9], 0, v[0:1]
	v_add_u32_e32 v6, 8, v20
	v_add_u32_e32 v8, 16, v20
	v_add_u32_e32 v10, 24, v20
	v_mad_i64_i32 v[4:5], s[8:9], v20, s83, v[2:3]
	v_mad_i64_i32 v[6:7], s[8:9], v6, s83, v[2:3]
	v_mad_i64_i32 v[8:9], s[8:9], v8, s83, v[2:3]
	v_mad_i64_i32 v[10:11], s[8:9], v10, s83, v[2:3]
	v_add_u32_e32 v12, 32, v20
	v_add_u32_e32 v14, 40, v20
	v_add_u32_e32 v16, 48, v20
	v_add_u32_e32 v20, 56, v20
	v_mad_i64_i32 v[12:13], s[8:9], v12, s83, v[2:3]
	v_mad_i64_i32 v[14:15], s[8:9], v14, s83, v[2:3]
	v_mad_i64_i32 v[16:17], s[8:9], v16, s83, v[2:3]
	v_mad_i64_i32 v[2:3], s[8:9], v20, s83, v[2:3]
	global_load_dword v4, v[4:5], off nt
	s_nop 0
	global_load_dword v5, v[6:7], off nt
	s_nop 0
	global_load_dword v6, v[8:9], off nt
	global_load_dword v7, v[10:11], off nt
	s_nop 0
	global_load_dword v8, v[12:13], off nt
	global_load_dword v9, v[14:15], off nt
	global_load_dword v10, v[16:17], off nt
	global_load_dword v11, v[2:3], off nt
	v_lshlrev_b32_e32 v3, 3, v18
	v_ashrrev_i32_e32 v2, 3, v18
	v_mul_lo_u32 v12, v19, s37
	v_and_b32_e32 v13, 56, v3
	v_lshlrev_b32_e32 v3, 2, v2
	v_add3_u32 v12, 0, v12, v0
	v_mul_u32_u24_e32 v0, 0x104, v13
	v_add3_u32 v14, 0, v0, v3
	v_add_u32_e32 v15, 0x400, v14
	v_add_u32_e32 v2, s6, v2
	v_ashrrev_i32_e32 v3, 31, v2
	v_lshlrev_b64 v[2:3], 11, v[2:3]
	v_lshl_add_u64 v[2:3], s[2:3], 0, v[2:3]
	s_ashr_i32 s5, s4, 31
	v_lshl_add_u64 v[2:3], s[4:5], 1, v[2:3]
	v_lshlrev_b32_e32 v0, 1, v13
	s_waitcnt vmcnt(7)
	ds_write_b32 v12, v4
	s_waitcnt vmcnt(6)
	ds_write_b32 v12, v5 offset:2080
	s_waitcnt vmcnt(5)
	ds_write_b32 v12, v6 offset:4160
	s_waitcnt vmcnt(4)
	ds_write_b32 v12, v7 offset:6240
	s_waitcnt vmcnt(3)
	ds_write_b32 v12, v8 offset:8320
	s_waitcnt vmcnt(2)
	ds_write_b32 v12, v9 offset:10400
	s_waitcnt vmcnt(1)
	ds_write_b32 v12, v10 offset:12480
	s_waitcnt vmcnt(0)
	ds_write_b32 v12, v11 offset:14560
	s_waitcnt lgkmcnt(0)
	s_barrier
	ds_read2_b32 v[4:5], v15 offset0:134 offset1:199
	ds_read2_b32 v[6:7], v15 offset0:4 offset1:69
	ds_read2_b32 v[8:9], v14 offset0:130 offset1:195
	ds_read2_b32 v[10:11], v14 offset1:65
	v_lshl_add_u64 v[12:13], v[2:3], 0, v[0:1]
	s_waitcnt lgkmcnt(3)
	v_cvt_pk_f16_f32 v5, v4, v5
	s_waitcnt lgkmcnt(2)
	v_cvt_pk_f16_f32 v4, v6, v7
	s_waitcnt lgkmcnt(1)
	v_cvt_pk_f16_f32 v3, v8, v9
	s_waitcnt lgkmcnt(0)
	v_cvt_pk_f16_f32 v2, v10, v11
	global_store_dwordx4 v[12:13], v[2:5], off
	s_barrier
	s_branch .LBB0_59
